# P0 hyena filter MLP stage 3 (f32 MFMA): 16 weight loads in flight per iteration instead of load-wait-MFMA serialisation, on top of v30
# speedup vs baseline: 1.0243x; 1.0083x over previous
.LBB0_32:
	v_lshl_add_u64 v[174:175], v[144:145], 0, s[8:9]
	v_add_u32_e32 v147, 0x2000, v141
	ds_read2_b32 v[176:177], v141 offset1:2
	ds_read2_b32 v[178:179], v147 offset0:32 offset1:34
	ds_read2_b32 v[186:187], v141 offset0:4 offset1:6
	ds_read2_b32 v[188:189], v147 offset0:36 offset1:38
	global_load_dword v216, v[174:175], off
	global_load_dword v217, v[174:175], off offset:128
	global_load_dword v218, v[174:175], off offset:256
	global_load_dword v219, v[174:175], off offset:384
	v_add_co_u32_e32 v182, vcc, 0x1000, v174
	s_nop 1
	v_addc_co_u32_e32 v183, vcc, 0, v175, vcc
	global_load_dword v220, v[182:183], off
	global_load_dword v221, v[182:183], off offset:128
	global_load_dword v222, v[182:183], off offset:256
	global_load_dword v223, v[182:183], off offset:384
	v_add_co_u32_e32 v180, vcc, 0x2000, v174
	s_nop 1
	v_addc_co_u32_e32 v181, vcc, 0, v175, vcc
	global_load_dword v224, v[180:181], off
	global_load_dword v225, v[180:181], off offset:128
	global_load_dword v226, v[180:181], off offset:256
	global_load_dword v227, v[180:181], off offset:384
	v_add_co_u32_e32 v184, vcc, 0x3000, v174
	s_nop 1
	v_addc_co_u32_e32 v185, vcc, 0, v175, vcc
	global_load_dword v228, v[184:185], off
	global_load_dword v229, v[184:185], off offset:128
	global_load_dword v230, v[184:185], off offset:256
	global_load_dword v231, v[184:185], off offset:384
	v_add_u32_e32 v141, 32, v141
	s_add_u32 s8, s8, 0x4000
	s_addc_u32 s9, s9, 0
	s_waitcnt lgkmcnt(0)
	s_waitcnt vmcnt(15)
	v_mfma_f32_32x32x2_f32 v[112:127], v176, v216, v[112:127]
	v_mfma_f32_32x32x2_f32 v[96:111], v178, v216, v[96:111]
	s_waitcnt vmcnt(14)
	v_mfma_f32_32x32x2_f32 v[80:95], v176, v217, v[80:95]
	v_mfma_f32_32x32x2_f32 v[64:79], v178, v217, v[64:79]
	s_waitcnt vmcnt(13)
	v_mfma_f32_32x32x2_f32 v[48:63], v176, v218, v[48:63]
	v_mfma_f32_32x32x2_f32 v[32:47], v178, v218, v[32:47]
	s_waitcnt vmcnt(12)
	v_mfma_f32_32x32x2_f32 v[16:31], v176, v219, v[16:31]
	v_mfma_f32_32x32x2_f32 v[0:15], v178, v219, v[0:15]
	s_waitcnt vmcnt(11)
	v_mfma_f32_32x32x2_f32 v[112:127], v177, v220, v[112:127]
	v_mfma_f32_32x32x2_f32 v[96:111], v179, v220, v[96:111]
	s_waitcnt vmcnt(10)
	v_mfma_f32_32x32x2_f32 v[80:95], v177, v221, v[80:95]
	v_mfma_f32_32x32x2_f32 v[64:79], v179, v221, v[64:79]
	s_waitcnt vmcnt(9)
	v_mfma_f32_32x32x2_f32 v[48:63], v177, v222, v[48:63]
	v_mfma_f32_32x32x2_f32 v[32:47], v179, v222, v[32:47]
	s_waitcnt vmcnt(8)
	v_mfma_f32_32x32x2_f32 v[16:31], v177, v223, v[16:31]
	v_mfma_f32_32x32x2_f32 v[0:15], v179, v223, v[0:15]
	s_waitcnt vmcnt(7)
	v_mfma_f32_32x32x2_f32 v[112:127], v186, v224, v[112:127]
	v_mfma_f32_32x32x2_f32 v[96:111], v188, v224, v[96:111]
	s_waitcnt vmcnt(6)
	v_mfma_f32_32x32x2_f32 v[80:95], v186, v225, v[80:95]
	v_mfma_f32_32x32x2_f32 v[64:79], v188, v225, v[64:79]
	s_waitcnt vmcnt(5)
	v_mfma_f32_32x32x2_f32 v[48:63], v186, v226, v[48:63]
	v_mfma_f32_32x32x2_f32 v[32:47], v188, v226, v[32:47]
	s_waitcnt vmcnt(4)
	v_mfma_f32_32x32x2_f32 v[16:31], v186, v227, v[16:31]
	v_mfma_f32_32x32x2_f32 v[0:15], v188, v227, v[0:15]
	s_waitcnt vmcnt(3)
	v_mfma_f32_32x32x2_f32 v[112:127], v187, v228, v[112:127]
	v_mfma_f32_32x32x2_f32 v[96:111], v189, v228, v[96:111]
	s_waitcnt vmcnt(2)
	v_mfma_f32_32x32x2_f32 v[80:95], v187, v229, v[80:95]
	v_mfma_f32_32x32x2_f32 v[64:79], v189, v229, v[64:79]
	s_waitcnt vmcnt(1)
	v_mfma_f32_32x32x2_f32 v[48:63], v187, v230, v[48:63]
	v_mfma_f32_32x32x2_f32 v[32:47], v189, v230, v[32:47]
	s_waitcnt vmcnt(0)
	v_mfma_f32_32x32x2_f32 v[16:31], v187, v231, v[16:31]
	v_mfma_f32_32x32x2_f32 v[0:15], v189, v231, v[0:15]
	s_cmp_eq_u32 s8, 0x20000
	s_cbranch_scc0 .LBB0_32
	v_div_scale_f32 v141, s[8:9], v146, v146, 1.0
	v_rcp_f32_e32 v143, v141
	s_and_b32 s41, s12, 0x80
	s_mul_i32 s1, s0, 0x1880
	v_or_b32_e32 v206, s41, v134
	v_fma_f32 v144, -v141, v143, 1.0
	v_fmac_f32_e32 v143, v144, v143
	v_div_scale_f32 v144, vcc, 1.0, v146, 1.0
	v_mul_f32_e32 v145, v144, v143
	v_fma_f32 v147, -v141, v145, v144
	v_fmac_f32_e32 v145, v147, v143
	v_fma_f32 v141, -v141, v145, v144
	v_div_fmas_f32 v141, v141, v143, v145
	s_add_i32 s0, s29, s1
	v_div_fixup_f32 v205, v141, v146, 1.0
	s_and_b32 s8, s20, 0x3fffff80
	v_cvt_f32_u32_e32 v141, v206
	s_cmpk_lg_i32 s8, 0x80
	s_cselect_b64 s[18:19], -1, 0
	s_cmpk_eq_i32 s8, 0x80
	s_cselect_b64 s[22:23], -1, 0
	s_cmpk_lt_u32 s12, 0x100
	s_cselect_b64 s[8:9], -1, 0
	s_lshl_b64 s[20:21], s[16:17], 22
	v_div_scale_f32 v143, s[16:17], s38, s38, v141
	v_rcp_f32_e32 v144, v143
	v_or_b32_e32 v209, s26, v134
	v_add_u32_e32 v188, s1, v169
	s_mov_b32 s24, 0
	v_fma_f32 v145, -v143, v144, 1.0
	v_fmac_f32_e32 v144, v145, v144
	v_div_scale_f32 v145, vcc, v141, s38, v141
	v_mul_f32_e32 v146, v145, v144
	v_fma_f32 v147, -v143, v146, v145
	v_fmac_f32_e32 v146, v147, v144
	v_fma_f32 v143, -v143, v146, v145
	v_div_fmas_f32 v143, v143, v144, v146
	v_div_fixup_f32 v141, v143, s38, v141
	v_fmamk_f32 v210, v141, 0x41447cbd, v170
	v_or_b32_e32 v141, s26, v151
	v_cvt_f32_i32_e32 v143, v141
	v_cmp_eq_u32_e32 vcc, 0, v141
	s_and_b64 s[16:17], vcc, s[22:23]
	v_cmp_ne_u32_e32 vcc, 0, v209
	v_mul_f32_e64 v143, v205, -v143
	v_mul_f32_e64 v144, v143, |v210|
	v_mul_f32_e32 v144, 0x3fb8aa3b, v144
	v_exp_f32_e32 v144, v144
	s_or_b64 s[18:19], s[18:19], vcc
	s_and_b64 s[22:23], s[14:15], exec
	s_cselect_b32 s22, s3, s21
	v_mul_f32_e32 v112, v144, v112
	v_cndmask_b32_e64 v207, v112, 0, s[16:17]
	v_lshlrev_b32_e32 v112, 2, v151
	v_add3_u32 v141, s0, v112, v171
	v_or_b32_e32 v112, s26, v152
	v_cvt_f32_i32_e32 v112, v112
	s_cselect_b32 s23, s2, s20
	s_cselect_b32 s3, s37, s35
	s_cselect_b32 s2, s36, s34
	v_mul_f32_e64 v173, v205, -v112
	v_mul_f32_e64 v112, v173, |v210|
	v_mul_f32_e32 v112, 0x3fb8aa3b, v112
	v_exp_f32_e32 v144, v112
	v_or_b32_e32 v112, s26, v153
	v_cvt_f32_i32_e32 v112, v112
	s_cselect_b32 s12, 9, 14
	v_or_b32_e32 v187, s41, v128
	v_mul_f32_e64 v175, v205, -v112
	v_mul_f32_e64 v112, v175, |v210|
	v_mul_f32_e32 v112, 0x3fb8aa3b, v112
	v_exp_f32_e32 v145, v112
	v_mov_b32_e32 v112, v113
	v_mov_b32_e32 v113, v114
	v_pk_mul_f32 v[144:145], v[144:145], v[112:113]
	v_or_b32_e32 v112, s26, v154
	v_cvt_f32_i32_e32 v112, v112
	ds_write2_b32 v141, v144, v145 offset0:1 offset1:2
	v_mul_f32_e64 v113, v205, -v112
	v_mul_f32_e64 v112, v113, |v210|
	v_mul_f32_e32 v112, 0x3fb8aa3b, v112
	v_exp_f32_e32 v112, v112
	s_nop 0
	v_mul_f32_e32 v208, v112, v115
	v_or_b32_e32 v112, s26, v155
	v_cvt_f32_i32_e32 v112, v112
	ds_write2_b32 v141, v207, v208 offset1:3
	v_mul_f32_e64 v174, v205, -v112
	v_mul_f32_e64 v112, v174, |v210|
	v_mul_f32_e32 v112, 0x3fb8aa3b, v112
	v_exp_f32_e32 v114, v112
	v_or_b32_e32 v112, s26, v156
	v_cvt_f32_i32_e32 v112, v112
	v_mul_f32_e64 v179, v205, -v112
	v_mul_f32_e64 v112, v179, |v210|
	v_mul_f32_e32 v112, 0x3fb8aa3b, v112
	v_exp_f32_e32 v115, v112
	v_or_b32_e32 v112, s26, v157
	v_cvt_f32_i32_e32 v112, v112
	v_pk_mul_f32 v[116:117], v[114:115], v[116:117]
	ds_write2_b32 v141, v116, v117 offset0:8 offset1:9
	v_mul_f32_e64 v177, v205, -v112
	v_mul_f32_e64 v112, v177, |v210|
	v_mul_f32_e32 v112, 0x3fb8aa3b, v112
	v_exp_f32_e32 v114, v112
	v_or_b32_e32 v112, s26, v158
	v_cvt_f32_i32_e32 v112, v112
	v_mul_f32_e64 v183, v205, -v112
	v_mul_f32_e64 v112, v183, |v210|
	v_mul_f32_e32 v112, 0x3fb8aa3b, v112
	v_exp_f32_e32 v115, v112
	v_or_b32_e32 v112, s26, v159
	v_cvt_f32_i32_e32 v112, v112
	v_pk_mul_f32 v[118:119], v[114:115], v[118:119]
	ds_write2_b32 v141, v118, v119 offset0:10 offset1:11
	v_mul_f32_e64 v176, v205, -v112
	v_mul_f32_e64 v112, v176, |v210|
	v_mul_f32_e32 v112, 0x3fb8aa3b, v112
	v_exp_f32_e32 v114, v112
	v_or_b32_e32 v112, s26, v160
	v_cvt_f32_i32_e32 v112, v112
	v_mul_f32_e64 v181, v205, -v112
	v_mul_f32_e64 v112, v181, |v210|
	v_mul_f32_e32 v112, 0x3fb8aa3b, v112
	v_exp_f32_e32 v115, v112
	v_or_b32_e32 v112, s26, v161
	v_cvt_f32_i32_e32 v112, v112
	v_pk_mul_f32 v[120:121], v[114:115], v[120:121]
	ds_write2_b32 v141, v120, v121 offset0:16 offset1:17
	v_mul_f32_e64 v180, v205, -v112
	v_mul_f32_e64 v112, v180, |v210|
	v_mul_f32_e32 v112, 0x3fb8aa3b, v112
	v_exp_f32_e32 v114, v112
	v_or_b32_e32 v112, s26, v162
	v_cvt_f32_i32_e32 v112, v112
	v_mul_f32_e64 v185, v205, -v112
	v_mul_f32_e64 v112, v185, |v210|
	v_mul_f32_e32 v112, 0x3fb8aa3b, v112
	v_exp_f32_e32 v115, v112
	v_or_b32_e32 v112, s26, v163
	v_cvt_f32_i32_e32 v112, v112
	v_pk_mul_f32 v[122:123], v[114:115], v[122:123]
	ds_write2_b32 v141, v122, v123 offset0:18 offset1:19
	v_mul_f32_e64 v178, v205, -v112
	v_mul_f32_e64 v112, v178, |v210|
	v_mul_f32_e32 v112, 0x3fb8aa3b, v112
	v_exp_f32_e32 v114, v112
	v_or_b32_e32 v112, s26, v164
	v_cvt_f32_i32_e32 v112, v112
	v_mul_f32_e64 v184, v205, -v112
	v_mul_f32_e64 v112, v184, |v210|
	v_mul_f32_e32 v112, 0x3fb8aa3b, v112
	v_exp_f32_e32 v115, v112
	v_or_b32_e32 v112, s26, v165
	v_cvt_f32_i32_e32 v112, v112
	v_pk_mul_f32 v[124:125], v[114:115], v[124:125]
	ds_write2_b32 v141, v124, v125 offset0:24 offset1:25
	v_mul_f32_e64 v182, v205, -v112
	v_mul_f32_e64 v112, v182, |v210|
	v_mul_f32_e32 v112, 0x3fb8aa3b, v112
	v_exp_f32_e32 v114, v112
	v_or_b32_e32 v112, s26, v166
	v_cvt_f32_i32_e32 v112, v112
	v_mul_f32_e64 v186, v205, -v112
	v_mul_f32_e64 v112, v186, |v210|
	v_mul_f32_e32 v112, 0x3fb8aa3b, v112
	v_exp_f32_e32 v115, v112
	v_sub_u32_e32 v112, 0, v209
	v_pk_mul_f32 v[126:127], v[114:115], v[126:127]
	v_cndmask_b32_e64 v114, v112, v209, s[8:9]
	v_ashrrev_i32_e32 v115, 31, v114
	v_lshl_add_u64 v[114:115], v[114:115], 2, s[2:3]
	v_mov_b32_e32 v112, v188
	ds_write2_b32 v141, v126, v127 offset0:26 offset1:27
	s_branch .LBB0_35
